# adds: fused HGRN2 chunk loop no longer drains its stores at every chunk start (the entry path waits once instead)
# speedup vs baseline: 1.0055x; 1.0055x over previous
; #define HL_LOADZ(gg) do { const size_t e_ = HL_E0(gg); _Pragma("unroll") for (int i = 0; i < 16; ++i) z[i] = HF[e_ + (size_t)i * 512]; } while (0)
; #define HL_LOADQ(gg) do { const size_t e_ = HL_E0(gg); _Pragma("unroll") for (int i = 0; i < 16; ++i) qv[i] = QE[e_ + (size_t)i * 512]; } while (0)
; #define HL_LOADH(gg) do { const bf16_t* hi_ = HIb + (size_t)(gg) * 64 * 512 + h * 128; _Pragma("unroll") for (int j = 0; j < 2; ++j) { const int idx = tid + 512 * j; hv[j] = *(const u32x4*)(hi_ + (size_t)(idx >> 4) * 512 + (idx & 15) * 8); } } while (0)
; __device__ __forceinline__ void hg_local_unit(const Params& P, LAS unsigned char* lds, int layer, int g0, int h, float* Sout, int tid, int lane, int wave) {
;     ...
;     HL_LOADZ(g0); HL_LOADQ(g0); HL_LOADH(g0);
.LBB0_801:
	v_ashrrev_i32_e32 v26, 7, v11
	v_ashrrev_i32_e64 v3, 31, s70
	v_mov_b32_e32 v2, s70
	s_waitcnt vmcnt(7)
	v_lshlrev_b32_e32 v72, 4, v26
	s_add_u32 s54, s88, s76
	s_waitcnt vmcnt(6)
	v_ashrrev_i32_e32 v73, 31, v72
	v_lshlrev_b64 v[4:5], 15, v[2:3]
	s_addc_u32 s55, s89, s77
	v_lshlrev_b64 v[6:7], 9, v[72:73]
	v_or_b32_e32 v4, v4, v12
	s_add_u32 s52, s54, 0x29f08000
	v_lshl_add_u64 v[4:5], v[4:5], 0, v[6:7]
	s_addc_u32 s53, s55, 0
	v_lshl_add_u64 v[4:5], v[4:5], 0, s[48:49]
	v_lshl_add_u64 v[6:7], v[4:5], 2, s[52:53]
	s_movk_i32 s3, 0x1000
	v_add_co_u32_e32 v8, vcc, s3, v6
	s_movk_i32 s6, 0x3000
	s_nop 0
	v_addc_co_u32_e32 v9, vcc, 0, v7, vcc
	v_add_co_u32_e32 v14, vcc, s56, v6
	s_movk_i32 s5, 0x5000
	s_nop 0
	v_addc_co_u32_e32 v15, vcc, 0, v7, vcc
	v_add_co_u32_e32 v16, vcc, s6, v6
	s_add_u32 s50, s54, 0x25e08000
	s_nop 0
	v_addc_co_u32_e32 v17, vcc, 0, v7, vcc
	v_add_co_u32_e32 v18, vcc, s57, v6
	s_addc_u32 s51, s55, 0
	s_nop 0
	v_addc_co_u32_e32 v19, vcc, 0, v7, vcc
	v_add_co_u32_e32 v20, vcc, s5, v6
	s_movk_i32 s5, 0x6000
	s_nop 0
	v_addc_co_u32_e32 v21, vcc, 0, v7, vcc
	v_add_co_u32_e32 v22, vcc, s5, v6
	s_movk_i32 s5, 0x7000
	s_nop 0
	v_addc_co_u32_e32 v23, vcc, 0, v7, vcc
	v_add_co_u32_e32 v24, vcc, s5, v6
	v_lshl_add_u64 v[4:5], v[4:5], 1, s[50:51]
	s_nop 0
	v_addc_co_u32_e32 v25, vcc, 0, v7, vcc
	global_load_dword v42, v[6:7], off
	global_load_dword v43, v[6:7], off offset:2048
	global_load_dword v44, v[8:9], off offset:2048
	global_load_dword v45, v[16:17], off offset:2048
	global_load_dword v49, v[20:21], off offset:2048
	global_load_dword v46, v[24:25], off
	global_load_dword v47, v[24:25], off offset:2048
	global_load_ushort v60, v[4:5], off
	v_add_co_u32_e32 v6, vcc, s3, v4
	s_add_u32 s40, s54, 0x36208000
	s_nop 0
	v_addc_co_u32_e32 v7, vcc, 0, v5, vcc
	s_addc_u32 s41, s55, 0
	v_add_co_u32_e32 v8, vcc, s56, v4
	v_lshlrev_b64 v[2:3], 16, v[2:3]
	s_nop 0
	v_addc_co_u32_e32 v9, vcc, 0, v5, vcc
	v_lshl_add_u64 v[2:3], s[40:41], 0, v[2:3]
	s_lshl_b64 s[56:57], s[48:49], 1
	v_lshlrev_b32_e32 v0, 4, v11
	v_ashrrev_i32_e32 v16, 4, v11
	global_load_dword v48, v[18:19], off offset:-4096
	global_load_dword v52, v[18:19], off
	global_load_dword v53, v[18:19], off offset:2048
	global_load_dword v54, v[22:23], off offset:-4096
	global_load_dword v50, v[22:23], off
	global_load_dword v51, v[22:23], off offset:2048
	global_load_ushort v61, v[8:9], off offset:-4096
	global_load_ushort v62, v[8:9], off
	global_load_ushort v63, v[8:9], off offset:1024
	global_load_ushort v64, v[8:9], off offset:2048
	global_load_ushort v65, v[8:9], off offset:3072
	v_add_co_u32_e32 v8, vcc, s6, v4
	v_lshl_add_u64 v[2:3], v[2:3], 0, s[56:57]
	v_and_b32_e32 v0, 0xf0, v0
	v_ashrrev_i32_e32 v17, 31, v16
	v_addc_co_u32_e32 v9, vcc, 0, v5, vcc
	global_load_ushort v66, v[4:5], off offset:1024
	global_load_ushort v67, v[4:5], off offset:2048
	global_load_ushort v68, v[4:5], off offset:3072
	global_load_ushort v69, v[6:7], off offset:1024
	global_load_ushort v108, v[6:7], off offset:2048
	global_load_ushort v109, v[6:7], off offset:3072
	global_load_ushort v110, v[8:9], off
	global_load_ushort v111, v[8:9], off offset:1024
	v_lshl_add_u64 v[6:7], v[2:3], 0, v[0:1]
	s_waitcnt vmcnt(31)
	v_lshlrev_b64 v[74:75], 10, v[16:17]
	v_lshl_add_u64 v[2:3], v[6:7], 0, v[74:75]
	global_load_ushort v139, v[8:9], off offset:2048
	global_load_ushort v140, v[8:9], off offset:3072
	s_nop 0
	global_load_dwordx4 v[2:5], v[2:3], off
	v_add_u32_e32 v8, 0x200, v11
	v_ashrrev_i32_e32 v18, 4, v8
	v_ashrrev_i32_e32 v19, 31, v18
	s_waitcnt vmcnt(32)
	v_lshlrev_b64 v[76:77], 10, v[18:19]
	v_lshl_add_u64 v[6:7], v[6:7], 0, v[76:77]
	global_load_dword v56, v[14:15], off offset:-4096
	global_load_dword v57, v[14:15], off
	global_load_dword v157, v[14:15], off offset:2048
	s_nop 0
	global_load_dwordx4 v[6:9], v[6:7], off
	s_add_u32 s12, s40, s56
	s_addc_u32 s13, s41, s57
	s_add_u32 s46, s50, s56
	s_addc_u32 s47, s51, s57
	v_lshlrev_b32_e32 v14, 1, v12
	v_mov_b32_e32 v15, v1
	s_movk_i32 s3, 0x80
	v_and_b32_e32 v70, 15, v10
	v_lshl_add_u64 v[88:89], s[46:47], 0, v[14:15]
	v_cmp_gt_u32_e64 s[46:47], s3, v11
	v_readlane_b32 s3, v243, 2
	v_ashrrev_i32_e32 v27, 4, v10
	v_lshlrev_b32_e32 v19, 2, v11
	s_waitcnt vmcnt(35)
	v_lshlrev_b32_e32 v80, 2, v12
	s_waitcnt vmcnt(34)
; __device__ __forceinline__ void hg_local_unit(const Params& P, LAS unsigned char* lds, int layer, int g0, int h, float* Sout, int tid, int lane, int wave) {
;     ...
;     const int k = tid & 127, tq = tid >> 7, fr = lane & 15, fq = lane >> 4;
;     float* HF = (float*)(ws + WS_HF); bf16_t* QE = (bf16_t*)(ws + WS_QE); const bf16_t* HIb = (const bf16_t*)(ws + WS_VTH); float* LG = (float*)(ws + WS_LG);
;     float lbv = 0.f;
;     if (layer > 0) lbv = __builtin_amdgcn_rcpf(1.f + __expf(hl[h * 128 + k] - hl[512 + h * 128 + k]));
;     const float oml = 1.f - lbv;
;     f32x4 S[8];
; #pragma unroll
;     for (int kb = 0; kb < 8; ++kb) S[kb] = (f32x4){0.f, 0.f, 0.f, 0.f};
	v_add_u32_e32 v85, 0, v14
	s_movk_i32 s5, 0x8e
	v_mov_b32_e32 v81, v1
	v_or_b32_e32 v11, s3, v70
	s_movk_i32 s11, 0x110
	v_mad_u32_u24 v21, v12, s5, v85
	v_lshl_add_u64 v[12:13], s[54:55], 0, v[80:81]
	s_mov_b64 s[54:55], 0x3af78c00
	v_mul_lo_u32 v11, v11, s11
	v_lshlrev_b32_e32 v82, 2, v27
	v_lshl_add_u64 v[92:93], v[12:13], 0, s[54:55]
	v_add_u32_e32 v12, 0, v11
	v_and_b32_e32 v87, -16, v10
	v_add_u32_e32 v13, s3, v82
	v_bfe_u32 v11, v10, 2, 2
	v_lshlrev_b32_e32 v10, 2, v10
	v_readlane_b32 s3, v243, 3
	v_lshlrev_b32_e32 v91, 3, v27
	s_lshl_b64 s[48:49], s[48:49], 2
	v_and_or_b32 v10, v10, 12, s3
	v_lshlrev_b32_e32 v97, 1, v10
	v_add_u32_e32 v10, 32, v91
	s_add_u32 s5, s52, s48
	v_or_b32_e32 v23, v91, v11
	v_or_b32_e32 v11, v10, v11
	s_addc_u32 s6, s53, s49
	s_lshl_b32 s94, s3, 2
	v_mul_lo_u32 v23, v23, s11
	v_mul_lo_u32 v11, v11, s11
	s_add_u32 s54, s5, s94
	v_add_u32_e32 v95, 0, v23
	v_add_u32_e32 v23, 0, v11
	v_lshlrev_b32_e32 v99, 1, v10
	s_addc_u32 s55, s6, 0
	v_lshlrev_b32_e32 v10, 2, v70
	v_mov_b32_e32 v11, v1
	v_lshl_add_u64 v[100:101], s[54:55], 0, v[10:11]
	v_lshlrev_b64 v[10:11], 11, v[72:73]
	v_lshl_add_u64 v[10:11], s[52:53], 0, v[10:11]
	v_lshl_add_u64 v[10:11], v[10:11], 0, s[48:49]
	v_lshl_add_u64 v[102:103], v[10:11], 0, v[80:81]
	v_lshlrev_b64 v[10:11], 10, v[72:73]
	v_lshl_add_u64 v[10:11], s[50:51], 0, v[10:11]
	v_readlane_b32 s14, v243, 51
	v_lshl_add_u64 v[10:11], v[10:11], 0, s[56:57]
	s_movk_i32 s3, 0x1100
	v_cmp_lt_i32_e64 s[40:41], 0, v26
	v_cmp_lt_i32_e64 s[42:43], 1, v26
	v_cmp_lt_i32_e64 s[44:45], 2, v26
	v_add_u32_e32 v20, s14, v14
	v_lshlrev_b32_e32 v22, 5, v26
	v_lshl_add_u64 v[106:107], v[10:11], 0, v[14:15]
	v_mul_lo_u32 v10, v18, s11
	v_mul_lo_u32 v81, v26, s3
	v_or_b32_e32 v11, s17, v70
	v_mov_b32_e32 v14, s14
	s_add_i32 s5, 0, 0x15a00
	v_or_b32_e32 v18, 1, v13
	v_or_b32_e32 v25, 2, v13
	v_or_b32_e32 v26, 3, v13
	v_mad_u32_u24 v112, v11, s11, v14
	v_lshl_add_u32 v15, v11, 1, s5
	v_cmp_gt_i32_e64 s[48:49], v11, v13
	v_cmp_gt_i32_e64 s[50:51], v11, v18
	v_cmp_gt_i32_e64 s[52:53], v11, v25
	v_cmp_gt_i32_e64 s[54:55], v11, v26
	v_or_b32_e32 v11, 16, v11
	v_cmp_gt_i32_e64 s[62:63], v11, v26
	v_mad_u32_u24 v114, v70, s11, 0
	v_lshl_or_b32 v26, v70, 7, v230
	v_sub_u32_e32 v26, v114, v26
	v_add_u32_e32 v17, 0, v0
	v_add_u32_e32 v86, 16, v82
	v_lshl_add_u64 v[104:105], s[12:13], 0, v[0:1]
	v_mul_lo_u32 v0, v16, s11
	v_mov_b32_e32 v14, s5
	s_movk_i32 s3, 0x90
	v_add_u32_e32 v98, 32, v82
	v_add_u32_e32 v96, 48, v82
	v_add_u32_e32 v94, 64, v82
	v_add_u32_e32 v90, 0x50, v82
	v_add_u32_e32 v84, 0x60, v82
	v_add_u32_e32 v78, 0x70, v82
	v_add_u32_e32 v119, 0x3300, v26
	v_mov_b32_e32 v26, s71
	v_add_u32_e32 v24, 0x2640, v95
	v_mul_lo_u32 v16, v13, s3
	v_add_u32_e32 v27, 0x1100, v112
	v_lshl_add_u32 v28, v11, 1, s5
	v_cmp_gt_i32_e64 s[56:57], v11, v13
	v_cmp_gt_i32_e64 s[58:59], v11, v18
	v_cmp_gt_i32_e64 s[60:61], v11, v25
	v_mad_u32_u24 v113, v70, s3, v14
	v_lshlrev_b32_e32 v11, 1, v86
	v_lshlrev_b32_e32 v13, 1, v98
	v_lshlrev_b32_e32 v14, 1, v96
	v_lshlrev_b32_e32 v18, 1, v94
	v_lshlrev_b32_e32 v25, 1, v90
	v_lshlrev_b32_e32 v29, 1, v84
	v_lshlrev_b32_e32 v30, 1, v78
	v_lshl_add_u32 v120, s70, 2, v26
	v_mov_b32_e32 v26, 0
	v_add_u32_e32 v121, v17, v0
	v_add_u32_e32 v0, 0, v19
	s_mov_b32 s34, 0
	s_movk_i32 s33, 0x1000
	s_movk_i32 s10, 0x2000
	s_movk_i32 s31, 0x3000
	v_sub_f32_e32 v79, 1.0, v71
	v_ashrrev_i32_e32 v83, 31, v82
	v_add_u32_e32 v115, 0x900, v113
	v_add_u32_e32 v116, 0x1200, v113
	v_add_u32_e32 v117, 0x1b00, v113
	v_mad_u32_u24 v118, v70, s3, 0
	v_add_u32_e32 v122, v17, v10
	v_add_u32_e32 v123, 0x17e00, v0
	v_add_u32_e32 v124, v20, v81
	v_add_u32_e32 v125, v21, v22
	v_add_u32_e32 v126, v12, v87
	v_add_u32_e32 v127, v15, v16
	v_add_u32_e32 v128, v27, v87
	v_add_u32_e32 v129, v28, v16
	v_add_u32_e32 v130, v23, v97
	v_add_u32_e32 v131, v24, v97
	v_add_u32_e32 v132, v114, v11
	v_add_u32_e32 v133, v114, v13
	v_add_u32_e32 v134, v114, v14
	v_add_u32_e32 v135, v114, v18
	v_add_u32_e32 v136, v114, v25
	v_add_u32_e32 v137, v114, v29
	v_add_u32_e32 v138, v114, v30
	v_mov_b32_e32 v27, v26
	v_mov_b32_e32 v28, v26
	v_mov_b32_e32 v29, v26
	v_mov_b32_e32 v38, v26
	v_mov_b32_e32 v39, v26
	v_mov_b32_e32 v40, v26
	v_mov_b32_e32 v41, v26
	v_mov_b32_e32 v34, v26
	v_mov_b32_e32 v35, v26
	v_mov_b32_e32 v36, v26
	v_mov_b32_e32 v37, v26
	v_mov_b32_e32 v30, v26
	v_mov_b32_e32 v31, v26
	v_mov_b32_e32 v32, v26
	v_mov_b32_e32 v33, v26
	v_mov_b32_e32 v22, v26
	v_mov_b32_e32 v23, v26
	v_mov_b32_e32 v24, v26
	v_mov_b32_e32 v25, v26
	v_mov_b32_e32 v14, v26
	v_mov_b32_e32 v15, v26
	v_mov_b32_e32 v16, v26
	v_mov_b32_e32 v17, v26
	v_mov_b32_e32 v18, v26
	v_mov_b32_e32 v19, v26
	v_mov_b32_e32 v20, v26
	v_mov_b32_e32 v21, v26
	v_mov_b32_e32 v10, v26
	v_mov_b32_e32 v11, v26
	v_mov_b32_e32 v12, v26
	v_mov_b32_e32 v13, v26
	s_waitcnt vmcnt(0)
	s_branch .LBB0_803

; #define LAS __attribute__((address_space(3)))
; __device__ __forceinline__ void hg_local_unit(const Params& P, LAS unsigned char* lds, int layer, int g0, int h, float* Sout, int tid, int lane, int wave) {
;     ...
;         for (int j = 0; j < 2; ++j) { const int idx = tid + 512 * j; *(LAS u32x4*)(lds + HL_VT + (idx >> 4) * 272 + (idx & 15) * 16) = hv[j]; }
;         float run = 0.f;
; #pragma unroll
;         for (int i = 0; i < 16; ++i) { const float zz = z[i]; const float e = __expf(-fabsf(zz)), r = __builtin_amdgcn_rcpf(1.f + e), er = e * r;
;             const float lf = (layer == 0) ? (fminf(zz, 0.f) - __logf(1.f + e)) : __logf(lbv + oml * (zz > 0.f ? r : er));
;             run += lf; bc[i] = run; kk[i] = oml * (zz > 0.f ? er : r); }
.LBB0_803:
	s_waitcnt vmcnt(33)
	v_mul_f32_e64 v0, |v42|, s30
	v_exp_f32_e32 v55, v0
	s_mov_b64 s[66:67], -1
	s_and_b64 vcc, exec, s[96:97]
	v_cmp_lt_f32_e64 s[64:65], 0, v42
	v_add_f32_e32 v58, 1.0, v55
	v_rcp_f32_e32 v0, v58
	ds_write_b128 v121, v[2:5] offset:35840
	ds_write_b128 v122, v[6:9] offset:35840
	v_mul_f32_e32 v158, v55, v0
	s_cbranch_vccz .LBB0_805
	v_cndmask_b32_e64 v55, v158, v0, s[64:65]
	v_fma_f32 v55, v79, v55, v71
	v_cmp_gt_f32_e32 vcc, s91, v55
	s_mov_b64 s[66:67], 0
	s_nop 0
	v_cndmask_b32_e64 v59, 0, 32, vcc
	v_ldexp_f32 v55, v55, v59
	v_log_f32_e32 v55, v55
	s_nop 0
	v_mul_f32_e32 v59, 0x3f317217, v55
	v_fma_f32 v59, v55, s29, -v59
	v_fmac_f32_e32 v59, 0x3377d1cf, v55
	v_fmac_f32_e32 v59, 0x3f317217, v55
	v_cmp_lt_f32_e64 s[64:65], |v55|, s28
	s_nop 1
	v_cndmask_b32_e64 v55, v55, v59, s[64:65]
	v_cndmask_b32_e32 v59, 0, v226, vcc
	v_sub_f32_e32 v55, v55, v59
